# RWKV scan loader waves: global loads for the next chunk issued one iteration early (separate register set), latency overlaps the chunk barrier
# speedup vs baseline: 1.0235x; 1.0060x over previous
; #define LAS __attribute__((address_space(3)))
; __device__ __forceinline__ float bflo(unsigned w) { return __uint_as_float(w << 16); }
; __device__ __forceinline__ void scan_load_chunk(LAS unsigned char* slot, const float* Wd, const float* V, const bf16_t* RKKB, int p, int rg, int s0, int lt) {
;     u32x4 r[7];
;     const size_t base = (size_t)p * SEQ + s0;
; #pragma unroll
;     for (int j = 0; j < 2; ++j) { const int idx = lt + 256 * j, st = idx >> 4, part = idx & 15; r[j] = *(const u32x4*)(Wd + (base + st) * 64 + part * 4); }
; #pragma unroll
;     for (int j = 2; j < 6; ++j) { const int k = lt + 256 * (j - 2), st = k >> 5, rem = k & 31, q = rem >> 3, part = rem & 7; r[j] = *(const u32x4*)(RKKB + ((base + st) * 4 + q) * 64 + part * 8); }
;     if (lt < 128) { const int st = lt >> 2, hf = lt & 3; r[6] = *(const u32x4*)(V + (base + st) * 64 + rg * 16 + hf * 4); }
; #pragma unroll
;     for (int j = 0; j < 2; ++j) { const int idx = lt + 256 * j, st = idx >> 4, part = idx & 15; *(LAS u32x4*)(slot + st * SCAN_STEP_B + part * 16) = r[j]; }
; #pragma unroll
;     for (int j = 2; j < 6; ++j) { const int k = lt + 256 * (j - 2), st = k >> 5, rem = k & 31, q = rem >> 3, part = rem & 7; const u32x4 w = r[j];
;         const int Q = (q == 0) ? 4 : (q == 1) ? 2 : (q == 2) ? 3 : 1;
;         LAS f32x4* d = (LAS f32x4*)(slot + st * SCAN_STEP_B + Q * 256 + part * 32);
;         d[0] = (f32x4){bflo(w.x), bfhi(w.x), bflo(w.y), bfhi(w.y)}; d[1] = (f32x4){bflo(w.z), bfhi(w.z), bflo(w.w), bfhi(w.w)}; }
;     if (lt < 128) { const int st = lt >> 2, hf = lt & 3; *(LAS u32x4*)(slot + st * SCAN_STEP_B + 1280 + hf * 16) = r[6]; }
; }
; __device__ __forceinline__ void rwkv_scan_unit(LAS unsigned char* lds, const float* Wd, const float* V, const bf16_t* RKKB, float* Yraw, int p, int rg, int tid) {
;     const int lane = tid & 63, wave = __builtin_amdgcn_readfirstlane(tid >> 6);
;     constexpr int NCH = SEQ / SCAN_CH;
;     scan_load_chunk(lds + (tid >> 8) * SCAN_SLOT_B, Wd, V, RKKB, p, rg, (tid >> 8) * SCAN_CH, tid & 255);
;     __syncthreads();
;     f32x4 S = (f32x4){0.f, 0.f, 0.f, 0.f};
;     const int kq = lane & 15, rl = wave * 4 + (lane >> 4);
;     for (int c = 0; c < NCH; ++c) {
;         if (wave >= 4) { if (c + 2 < NCH) scan_load_chunk(lds + ((c + 2) % 3) * SCAN_SLOT_B, Wd, V, RKKB, p, rg, (c + 2) * SCAN_CH, tid - 256); }
.LBB0_340:
	s_or_b64 exec, exec, s[6:7]
	v_add3_u32 v14, v14, v10, v22
	s_waitcnt vmcnt(0)
	v_lshlrev_b32_e32 v10, 16, v2
	v_and_b32_e32 v11, 0xffff0000, v2
	v_lshlrev_b32_e32 v12, 16, v3
	v_and_b32_e32 v13, 0xffff0000, v3
	v_lshlrev_b32_e32 v2, 16, v4
	v_and_b32_e32 v3, 0xffff0000, v4
	v_lshlrev_b32_e32 v4, 16, v5
	v_and_b32_e32 v5, 0xffff0000, v5
	ds_write_b128 v14, v[10:13] offset:10752
	ds_write_b128 v14, v[2:5] offset:10768
	s_and_saveexec_b64 s[6:7], s[4:5]
	v_lshrrev_b32_e32 v2, 8, v232
	v_lshlrev_b32_e32 v2, 11, v2
	v_and_b32_e32 v3, 3, v232
	v_lshl_or_b32 v2, v3, 9, v2
	v_and_b32_e32 v3, 0xfc, v232
	v_or_b32_e32 v2, v2, v3
	v_add_u32_e32 v2, 0x1f800, v2
	ds_write_b32 v2, v6
	ds_write_b32 v2, v7 offset:128
	ds_write_b32 v2, v8 offset:256
	ds_write_b32 v2, v9 offset:384
	s_or_b64 exec, exec, s[6:7]
	v_and_b32_e32 v3, 4, v32
	v_cmp_eq_u32_e64 s[6:7], 0, v3
	v_and_b32_e32 v3, 1, v32
	s_ashr_i32 s4, s10, 6
	v_and_b32_e32 v4, 2, v32
	v_cmp_eq_u32_e64 s[10:11], 0, v3
	v_add_u32_e32 v3, 0xffffff00, v32
	v_add_u32_e32 v12, 0x100, v32
	v_add_u32_e32 v14, 0x200, v32
	s_cmp_lt_i32 s4, 4
	v_cmp_eq_u32_e64 s[8:9], 0, v4
	v_ashrrev_i32_e32 v4, 4, v3
	v_ashrrev_i32_e32 v6, 4, v32
	v_ashrrev_i32_e32 v8, 5, v3
	v_ashrrev_i32_e32 v10, 5, v32
	v_ashrrev_i32_e32 v12, 5, v12
	v_ashrrev_i32_e32 v14, 5, v14
	v_ashrrev_i32_e32 v16, 2, v3
	s_movk_i32 s19, 0x540
	s_cselect_b64 s[16:17], -1, 0
	v_mul_lo_u32 v74, v4, s19
	v_mul_lo_u32 v75, v6, s19
	v_mul_lo_u32 v77, v8, s19
	v_mul_lo_u32 v78, v10, s19
	v_mul_lo_u32 v79, v12, s19
	v_mul_lo_u32 v80, v14, s19
	v_mul_lo_u32 v81, v16, s19
	s_and_b32 s23, s20, 7
	s_ashr_i32 s19, s18, 31
	s_lshl_b32 s21, s23, 22
	s_lshl_b64 s[24:25], s[18:19], 20
	v_ashrrev_i32_e32 v17, 31, v16
	v_lshlrev_b32_e32 v19, 5, v32
	s_add_u32 s24, s21, s24
	v_and_b32_e32 v76, 0xe0, v19
	s_addc_u32 s25, 0, s25
	v_lshlrev_b64 v[16:17], 8, v[16:17]
	s_lshl_b32 s20, s20, 3
	v_and_b32_e32 v19, 3, v3
	v_lshl_add_u64 v[16:17], s[24:25], 0, v[16:17]
	s_and_b32 s26, s20, 0xc0
	v_lshlrev_b32_e32 v19, 4, v19
	v_readlane_b32 s20, v254, 47
	v_or3_b32 v16, v16, s26, v19
	v_readlane_b32 s21, v254, 48
	s_lshl_b32 s27, s23, 23
	v_ashrrev_i32_e32 v5, 31, v4
	v_lshl_add_u64 v[46:47], s[20:21], 0, v[16:17]
	s_lshl_b64 s[20:21], s[18:19], 21
	v_ashrrev_i32_e32 v7, 31, v6
	v_ashrrev_i32_e32 v9, 31, v8
	v_ashrrev_i32_e32 v11, 31, v10
	v_ashrrev_i32_e32 v13, 31, v12
	v_ashrrev_i32_e32 v15, 31, v14
	s_add_u32 s20, s27, s20
	v_lshlrev_b32_e32 v18, 4, v3
	s_addc_u32 s21, 0, s21
	v_lshlrev_b64 v[14:15], 9, v[14:15]
	v_lshlrev_b64 v[12:13], 9, v[12:13]
	v_lshlrev_b64 v[10:11], 9, v[10:11]
	v_lshlrev_b64 v[8:9], 9, v[8:9]
	v_lshlrev_b64 v[6:7], 8, v[6:7]
	v_lshlrev_b64 v[4:5], 8, v[4:5]
	v_and_b32_e32 v73, 0xf0, v18
	v_lshl_add_u64 v[14:15], s[20:21], 0, v[14:15]
	v_lshl_add_u64 v[12:13], s[20:21], 0, v[12:13]
	v_lshl_add_u64 v[10:11], s[20:21], 0, v[10:11]
	v_lshl_add_u64 v[8:9], s[20:21], 0, v[8:9]
	v_lshl_add_u64 v[6:7], s[24:25], 0, v[6:7]
	v_readlane_b32 s20, v254, 51
	v_lshl_add_u64 v[4:5], s[24:25], 0, v[4:5]
	v_or_b32_e32 v6, v6, v73
	v_readlane_b32 s21, v254, 52
	v_or_b32_e32 v4, v4, v73
	s_lshl_b64 s[18:19], s[18:19], 12
	v_lshl_add_u64 v[56:57], s[20:21], 0, v[6:7]
	v_lshl_add_u64 v[58:59], s[20:21], 0, v[4:5]
	s_lshl_b32 s20, s23, 14
	s_add_u32 s18, s20, s18
	v_and_b32_e32 v0, 15, v32
	s_addc_u32 s19, 0, s19
	v_bfe_u32 v2, v32, 4, 2
	v_and_b32_e32 v3, 7, v3
	v_or_b32_e32 v4, s18, v0
	v_mov_b32_e32 v5, s19
	v_lshl_or_b32 v2, s4, 2, v2
	v_and_b32_e32 v16, 0x180, v18
	v_lshlrev_b32_e32 v3, 4, v3
	v_lshlrev_b64 v[4:5], 8, v[4:5]
	v_or3_b32 v14, v14, v16, v3
	v_or3_b32 v12, v12, v16, v3
	v_or3_b32 v10, v10, v16, v3
	v_or3_b32 v8, v8, v16, v3
	v_or_b32_e32 v4, s26, v4
	v_ashrrev_i32_e32 v3, 31, v2
	v_lshlrev_b32_e32 v72, 2, v2
	v_lshl_add_u64 v[2:3], v[2:3], 2, v[4:5]
	v_readlane_b32 s28, v254, 49
	v_lshl_add_u64 v[60:61], s[92:93], 0, v[2:3]
	v_mov_b32_e32 v2, v1
	v_mov_b32_e32 v3, v1
	v_lshlrev_b32_e32 v71, 4, v0
	v_cmp_gt_u32_e64 s[4:5], 8, v0
	s_movk_i32 s12, 0x180
	v_readlane_b32 s29, v254, 50
	v_mov_b32_e32 v0, v1
	v_mov_b64_e32 v[4:5], v[2:3]
	s_mov_b32 s22, 0
	v_cmp_gt_i32_e64 s[12:13], s12, v32
	v_and_b32_e32 v82, 48, v18
	v_lshl_add_u64 v[48:49], s[28:29], 0, v[14:15]
	v_lshl_add_u64 v[50:51], s[28:29], 0, v[12:13]
	v_lshl_add_u64 v[52:53], s[28:29], 0, v[10:11]
	v_lshl_add_u64 v[54:55], s[28:29], 0, v[8:9]
	v_mov_b64_e32 v[2:3], v[0:1]
	s_waitcnt lgkmcnt(0)
	s_barrier
	s_and_b64 vcc, exec, s[16:17]
	s_cbranch_vccz .Lscan_ldprime
	s_setprio 3
	v_lshlrev_b32_e32 v96, 5, v72
	v_add_u32_e32 v96, 0x1f800, v96
	ds_read_b128 v[116:119], v96
	ds_read_b128 v[132:135], v71 offset:768
	ds_read_b128 v[120:123], v71
	ds_read_b128 v[128:131], v71 offset:512
	ds_read_b128 v[124:127], v71 offset:256
	ds_read_b128 v[136:139], v71 offset:1024
	ds_read_b128 v[156:159], v71 offset:2112
	ds_read_b128 v[144:147], v71 offset:1344
	ds_read_b128 v[152:155], v71 offset:1856
	ds_read_b128 v[148:151], v71 offset:1600
	ds_read_b128 v[160:163], v71 offset:2368
	s_branch .Lscan_noprime
.Lscan_ldprime:
	v_lshl_add_u64 v[134:135], v[58:59], 0, s[14:15]
	global_load_dwordx4 v[130:133], v[134:135], off
	v_lshl_add_u64 v[134:135], v[56:57], 0, s[14:15]
	global_load_dwordx4 v[126:129], v[134:135], off
	v_lshl_add_u64 v[134:135], v[54:55], 0, s[14:15]
	global_load_dwordx4 v[122:125], v[134:135], off
	v_lshl_add_u64 v[134:135], v[52:53], 0, s[14:15]
	global_load_dwordx4 v[118:121], v[134:135], off
	v_lshl_add_u64 v[134:135], v[50:51], 0, s[14:15]
	global_load_dwordx4 v[114:117], v[134:135], off
	v_lshl_add_u64 v[134:135], v[48:49], 0, s[14:15]
	global_load_dwordx4 v[106:109], v[134:135], off
	v_mov_b32_e32 v110, 0
	v_mov_b32_e32 v111, 0
	v_mov_b32_e32 v112, 0
	v_mov_b32_e32 v113, 0
	s_and_saveexec_b64 s[18:19], s[12:13]
	v_lshl_add_u64 v[134:135], v[46:47], 0, s[14:15]
	global_load_dwordx4 v[110:113], v[134:135], off
	s_or_b64 exec, exec, s[18:19]

; __device__ __forceinline__ void scan_load_chunk(LAS unsigned char* slot, const float* Wd, const float* V, const bf16_t* RKKB, int p, int rg, int s0, int lt) {
;     ...
;     for (int j = 0; j < 2; ++j) { const int idx = lt + 256 * j, st = idx >> 4, part = idx & 15; r[j] = *(const u32x4*)(Wd + (base + st) * 64 + part * 4); }
; #pragma unroll
;     for (int j = 2; j < 6; ++j) { const int k = lt + 256 * (j - 2), st = k >> 5, rem = k & 31, q = rem >> 3, part = rem & 7; r[j] = *(const u32x4*)(RKKB + ((base + st) * 4 + q) * 64 + part * 8); }
;     if (lt < 128) { const int st = lt >> 2, hf = lt & 3; r[6] = *(const u32x4*)(V + (base + st) * 64 + rg * 16 + hf * 4); }
; __device__ __forceinline__ void rwkv_scan_unit(LAS unsigned char* lds, const float* Wd, const float* V, const bf16_t* RKKB, float* Yraw, int p, int rg, int tid) {
;     ...
;     for (int c = 0; c < NCH; ++c) {
;         if (wave >= 4) { if (c + 2 < NCH) scan_load_chunk(lds + ((c + 2) % 3) * SCAN_SLOT_B, Wd, V, RKKB, p, rg, (c + 2) * SCAN_CH, tid - 256); }
.LBB0_345:
	s_add_i32 s22, s22, 1
	s_mov_b64 s[18:19], 0x2000
	s_mov_b64 s[20:21], 0x4000
	v_mov_b64_e32 v[2:3], v[6:7]
	v_lshl_add_u64 v[46:47], v[46:47], 0, s[18:19]
	v_lshl_add_u64 v[48:49], v[48:49], 0, s[20:21]
	v_lshl_add_u64 v[50:51], v[50:51], 0, s[20:21]
	v_lshl_add_u64 v[52:53], v[52:53], 0, s[20:21]
	v_lshl_add_u64 v[54:55], v[54:55], 0, s[20:21]
	v_lshl_add_u64 v[56:57], v[56:57], 0, s[18:19]
	v_lshl_add_u64 v[58:59], v[58:59], 0, s[18:19]
	s_mov_b64 s[68:69], 0x2000
	v_lshl_add_u64 v[60:61], v[60:61], 0, s[18:19]
	s_cmpk_gt_u32 s22, 0x7d
	s_cbranch_scc1 .Lscan_ld_skip
	v_lshl_add_u64 v[134:135], v[58:59], 0, s[14:15]
	global_load_dwordx4 v[130:133], v[134:135], off
	v_lshl_add_u64 v[134:135], v[56:57], 0, s[14:15]
	global_load_dwordx4 v[126:129], v[134:135], off
	v_lshl_add_u64 v[134:135], v[54:55], 0, s[14:15]
	global_load_dwordx4 v[122:125], v[134:135], off
	v_lshl_add_u64 v[134:135], v[52:53], 0, s[14:15]
	global_load_dwordx4 v[118:121], v[134:135], off
	v_lshl_add_u64 v[134:135], v[50:51], 0, s[14:15]
	global_load_dwordx4 v[114:117], v[134:135], off
	v_lshl_add_u64 v[134:135], v[48:49], 0, s[14:15]
	global_load_dwordx4 v[106:109], v[134:135], off
	v_mov_b32_e32 v110, 0
	v_mov_b32_e32 v111, 0
	v_mov_b32_e32 v112, 0
	v_mov_b32_e32 v113, 0
	s_and_saveexec_b64 s[18:19], s[12:13]
	v_lshl_add_u64 v[134:135], v[46:47], 0, s[14:15]
	global_load_dwordx4 v[110:113], v[134:135], off
	s_or_b64 exec, exec, s[18:19]
.Lscan_ld_skip:
	s_cmpk_eq_i32 s22, 0x80
	v_mov_b64_e32 v[4:5], v[8:9]
	s_waitcnt lgkmcnt(0)
	s_barrier
	s_cbranch_scc1 .LBB0_370

; #define LAS __attribute__((address_space(3)))
; __device__ __forceinline__ float bflo(unsigned w) { return __uint_as_float(w << 16); }
; __device__ __forceinline__ float bfhi(unsigned w) { return __uint_as_float(w & 0xffff0000u); }
; __device__ __forceinline__ void scan_load_chunk(LAS unsigned char* slot, const float* Wd, const float* V, const bf16_t* RKKB, int p, int rg, int s0, int lt) {
;     ...
;     for (int j = 0; j < 2; ++j) { const int idx = lt + 256 * j, st = idx >> 4, part = idx & 15; r[j] = *(const u32x4*)(Wd + (base + st) * 64 + part * 4); }
; #pragma unroll
;     for (int j = 2; j < 6; ++j) { const int k = lt + 256 * (j - 2), st = k >> 5, rem = k & 31, q = rem >> 3, part = rem & 7; r[j] = *(const u32x4*)(RKKB + ((base + st) * 4 + q) * 64 + part * 8); }
;     if (lt < 128) { const int st = lt >> 2, hf = lt & 3; r[6] = *(const u32x4*)(V + (base + st) * 64 + rg * 16 + hf * 4); }
; #pragma unroll
;     for (int j = 0; j < 2; ++j) { const int idx = lt + 256 * j, st = idx >> 4, part = idx & 15; *(LAS u32x4*)(slot + st * SCAN_STEP_B + part * 16) = r[j]; }
; #pragma unroll
;     for (int j = 2; j < 6; ++j) { const int k = lt + 256 * (j - 2), st = k >> 5, rem = k & 31, q = rem >> 3, part = rem & 7; const u32x4 w = r[j];
;         const int Q = (q == 0) ? 4 : (q == 1) ? 2 : (q == 2) ? 3 : 1;
;         LAS f32x4* d = (LAS f32x4*)(slot + st * SCAN_STEP_B + Q * 256 + part * 32);
;         d[0] = (f32x4){bflo(w.x), bfhi(w.x), bflo(w.y), bfhi(w.y)}; d[1] = (f32x4){bflo(w.z), bfhi(w.z), bflo(w.w), bfhi(w.w)}; }
;     if (lt < 128) { const int st = lt >> 2, hf = lt & 3; *(LAS u32x4*)(slot + st * SCAN_STEP_B + 1280 + hf * 16) = r[6]; }
.LBB0_348:
	s_andn2_b64 vcc, exec, s[18:19]
	s_cbranch_vccnz .LBB0_345
	s_cmpk_gt_u32 s22, 0x7d
	s_cbranch_scc1 .LBB0_344
	s_add_i32 s18, s22, 2
	s_mul_i32 s19, s18, 0xab
	s_bfe_u32 s19, s19, 0x70009
	s_mul_i32 s19, s19, 3
	s_sub_i32 s18, s18, s19
	s_and_b32 s18, s18, 0xff
	s_mul_i32 s18, s18, 0xa800
	s_add_i32 s23, s18, 0
	v_add_u32_e32 v0, s23, v73
	v_add_u32_e32 v34, v0, v74
	v_add_u32_e32 v0, v0, v75
	s_waitcnt vmcnt(0)
	ds_write_b128 v34, v[130:133]
	ds_write_b128 v0, v[126:129]
	v_cmp_lt_i32_e32 vcc, 0, v69
	v_mov_b32_e32 v0, 0x400
	s_and_saveexec_b64 s[18:19], vcc
	s_cbranch_execz .LBB0_356
	v_cmp_ne_u32_e32 vcc, 1, v69
	s_and_saveexec_b64 s[20:21], vcc
	s_xor_b64 s[20:21], exec, s[20:21]
	s_or_saveexec_b64 s[20:21], s[20:21]
	v_mov_b32_e32 v0, v70
	s_xor_b64 exec, exec, s[20:21]
	v_mov_b32_e32 v0, 0x200
	s_or_b64 exec, exec, s[20:21]
.LBB0_356:
	s_or_b64 exec, exec, s[18:19]
	v_add_u32_e32 v26, s23, v77
	v_add3_u32 v0, v26, v0, v76
	v_lshlrev_b32_e32 v26, 16, v122
	v_and_b32_e32 v27, 0xffff0000, v122
	v_lshlrev_b32_e32 v28, 16, v123
	v_and_b32_e32 v29, 0xffff0000, v123
	v_lshlrev_b32_e32 v22, 16, v124
	v_and_b32_e32 v23, 0xffff0000, v124
	v_lshlrev_b32_e32 v24, 16, v125
	v_and_b32_e32 v25, 0xffff0000, v125
	ds_write_b128 v0, v[26:29]
	ds_write_b128 v0, v[22:25] offset:16
	v_cmp_lt_i32_e32 vcc, 0, v69
	v_mov_b32_e32 v0, 0x400
	s_and_saveexec_b64 s[18:19], vcc
	s_cbranch_execz .LBB0_360
	v_cmp_ne_u32_e32 vcc, 1, v69
	s_and_saveexec_b64 s[20:21], vcc
	s_xor_b64 s[20:21], exec, s[20:21]
	s_or_saveexec_b64 s[20:21], s[20:21]
	v_mov_b32_e32 v0, v70
	s_xor_b64 exec, exec, s[20:21]
	v_mov_b32_e32 v0, 0x200
	s_or_b64 exec, exec, s[20:21]
.LBB0_360:
	s_or_b64 exec, exec, s[18:19]
	v_add_u32_e32 v22, s23, v78
	v_add3_u32 v0, v22, v0, v76
	v_lshlrev_b32_e32 v22, 16, v118
	v_and_b32_e32 v23, 0xffff0000, v118
	v_lshlrev_b32_e32 v24, 16, v119
	v_and_b32_e32 v25, 0xffff0000, v119
	v_lshlrev_b32_e32 v18, 16, v120
	v_and_b32_e32 v19, 0xffff0000, v120
	v_lshlrev_b32_e32 v20, 16, v121
	v_and_b32_e32 v21, 0xffff0000, v121
	ds_write_b128 v0, v[22:25]
	ds_write_b128 v0, v[18:21] offset:16
	v_cmp_lt_i32_e32 vcc, 0, v69
	v_mov_b32_e32 v0, 0x400
	s_and_saveexec_b64 s[18:19], vcc
	s_cbranch_execz .LBB0_364
	v_cmp_ne_u32_e32 vcc, 1, v69
	s_and_saveexec_b64 s[20:21], vcc
	s_xor_b64 s[20:21], exec, s[20:21]
	s_or_saveexec_b64 s[20:21], s[20:21]
	v_mov_b32_e32 v0, v70
	s_xor_b64 exec, exec, s[20:21]
	v_mov_b32_e32 v0, 0x200
	s_or_b64 exec, exec, s[20:21]
.LBB0_364:
	s_or_b64 exec, exec, s[18:19]
	v_add_u32_e32 v18, s23, v79
	v_add3_u32 v0, v18, v0, v76
	v_lshlrev_b32_e32 v18, 16, v114
	v_and_b32_e32 v19, 0xffff0000, v114
	v_lshlrev_b32_e32 v20, 16, v115
	v_and_b32_e32 v21, 0xffff0000, v115
	v_lshlrev_b32_e32 v14, 16, v116
	v_and_b32_e32 v15, 0xffff0000, v116
	v_lshlrev_b32_e32 v16, 16, v117
	v_and_b32_e32 v17, 0xffff0000, v117
	ds_write_b128 v0, v[18:21]
	ds_write_b128 v0, v[14:17] offset:16
	v_cmp_lt_i32_e32 vcc, 0, v69
	v_mov_b32_e32 v0, 0x400
	s_and_saveexec_b64 s[18:19], vcc
	s_cbranch_execz .LBB0_368
	v_cmp_ne_u32_e32 vcc, 1, v69
	s_and_saveexec_b64 s[20:21], vcc
	s_xor_b64 s[20:21], exec, s[20:21]
	s_or_saveexec_b64 s[20:21], s[20:21]
	v_mov_b32_e32 v0, v70
	s_xor_b64 exec, exec, s[20:21]
	v_mov_b32_e32 v0, 0x200
	s_or_b64 exec, exec, s[20:21]
.LBB0_368:
	s_or_b64 exec, exec, s[18:19]
	v_add_u32_e32 v14, s23, v80
	v_add3_u32 v0, v14, v0, v76
	v_lshlrev_b32_e32 v14, 16, v106
	v_and_b32_e32 v15, 0xffff0000, v106
	v_lshlrev_b32_e32 v16, 16, v107
	v_and_b32_e32 v17, 0xffff0000, v107
	v_lshlrev_b32_e32 v6, 16, v108
	v_and_b32_e32 v7, 0xffff0000, v108
	v_lshlrev_b32_e32 v8, 16, v109
	v_and_b32_e32 v9, 0xffff0000, v109
	ds_write_b128 v0, v[14:17]
	ds_write_b128 v0, v[6:9] offset:16
	s_and_saveexec_b64 s[18:19], s[12:13]
	s_cbranch_execz .LBB0_343
	s_lshr_b32 s20, s23, 15
	s_lshl_b32 s20, s20, 11
	s_add_i32 s20, s20, 0x1f800
	v_and_b32_e32 v14, 0xfc, v232
	v_and_b32_e32 v0, 3, v232
	v_lshl_or_b32 v0, v0, 9, v14
	v_add_u32_e32 v0, s20, v0
	ds_write_b32 v0, v110
	ds_write_b32 v0, v111 offset:128
	ds_write_b32 v0, v112 offset:256
	ds_write_b32 v0, v113 offset:384
	s_branch .LBB0_343
